# MLA loop rewritten: QK1 overlapped with softmax0, PV0 with softmax1, in-place exp+pack, K prefetch across barrier, DMA pieces between MFMAs
# speedup vs baseline: 1.0087x; 1.0087x over previous
; DEV void mla_unit(PG8_LAS unsigned char* lds, const bf16_t* Q, const bf16_t* K, const bf16_t* VT, bf16_t* O) {
;     ...
;     const int krow = 16 * (r32 >> 4) + 8 * ((r32 >> 2) & 1) + 4 * ((r32 >> 3) & 1) + (r32 & 3);
;     const int kfo = (krow * 13 + hi) * 16, vfo = KBY + (r32 * 9 + hi) * 16;
;     __syncthreads();
;     for (int t = 0; t < NT; ++t) {
;         const int cur = t & 1;
;         if (t + 1 < NT) MLA_DMA((t + 1) * 64, cur ^ 1);
;         PG8_LAS const unsigned char* Kb = lds + cur * BUFB;
;         bf16x8 pb[2][4];
; #pragma unroll
;         for (int sb = 0; sb < 2; ++sb) {
;             f32x16 p0, p1; int kfo_ = kfo; asm volatile("" : "+v"(kfo_));
; #pragma unroll
;             for (int d0 = 0; d0 < 6; ++d0) {
;                 const bf16x8 k0 = *(PG8_LAS const bf16x8*)(Kb + kfo_ + d0 * 32), k1 = *(PG8_LAS const bf16x8*)(Kb + kfo_ + 32 * 208 + d0 * 32);
;                 p0 = __builtin_amdgcn_mfma_f32_32x32x16_bf16(k0, qf[sb][d0], d0 == 0 ? negm[sb] : p0, 0, 0, 0);
;                 p1 = __builtin_amdgcn_mfma_f32_32x32x16_bf16(k1, qf[sb][d0], d0 == 0 ? negm[sb] : p1, 0, 0, 0);
;             }
;             asm volatile("s_nop 15\n\ts_nop 7" : "+v"(p0), "+v"(p1));
;             float mx = max3f(p0[0], p1[0], p0[1]);
; #pragma unroll
;             for (int r = 1; r < 15; ++r) mx = max3f(mx, p1[r], p0[r + 1]);
;             mx = hmax32(fmaxf(mx, p1[15]));
;             if (t == 0 || __any(mx > 8.f)) {
;                 const float dl = (t == 0) ? mx : fmaxf(mx, 0.f); mhat[sb] += dl;
; #pragma unroll
;                 for (int r = 0; r < 16; ++r) { p0[r] -= dl; p1[r] -= dl; negm[sb][r] = -mhat[sb]; }
;                 if (t != 0) { const float f = __builtin_amdgcn_exp2f(-dl); lrun[sb] *= f;
; #pragma unroll
;                     for (int r = 0; r < 16; ++r) { o[sb][0][r] *= f; o[sb][1][r] *= f; } }
;             }
;             float rsum = 0.f;
; #pragma unroll
;             for (int r = 0; r < 16; ++r) { p0[r] = __builtin_amdgcn_exp2f(p0[r]); p1[r] = __builtin_amdgcn_exp2f(p1[r]); rsum += p0[r] + p1[r]; }
;             lrun[sb] += rsum;
; #pragma unroll
;             for (int ks = 0; ks < 4; ++ks) { u32x4 w;
;                 if (ks < 2) { w.x = pk2(p0[8 * ks + 0], p0[8 * ks + 1]); w.y = pk2(p0[8 * ks + 2], p0[8 * ks + 3]); w.z = pk2(p0[8 * ks + 4], p0[8 * ks + 5]); w.w = pk2(p0[8 * ks + 6], p0[8 * ks + 7]); }
.LBB0_1248:
	v_lshlrev_b32_e32 v1, 1, v0
	v_lshrrev_b32_e32 v2, 1, v0
	v_and_b32_e32 v1, 8, v1
	v_and_b32_e32 v2, 4, v2
	v_and_b32_e32 v0, 19, v0
	v_or3_b32 v0, v0, v1, v2
	v_mul_u32_u24_e32 v0, 13, v0
	v_add_lshl_u32 v194, v0, v129, 4
	v_mov_b32_e32 v0, v194
	v_mul_u32_u24_e32 v36, 9, v36
	v_add_u32_e32 v37, 0, v0
	ds_read_b128 v[0:3], v37
	ds_read_b128 v[32:35], v37 offset:32
	s_waitcnt lgkmcnt(0)
	v_mfma_f32_32x32x16_bf16 v[0:15], v[0:3], v[130:133], 0
	ds_read_b128 v[16:19], v37 offset:6656
	ds_read_b128 v[38:41], v37 offset:6688
	v_add_lshl_u32 v195, v36, v129, 4
	v_add_u32_e32 v112, 0, v195
	s_lshl_b32 s5, s54, 10
	s_add_u32 s20, s55, s20
	s_addc_u32 s21, 0, s21
	s_add_u32 s20, s20, 0x13000100
	s_waitcnt lgkmcnt(0)
	v_mfma_f32_32x32x16_bf16 v[16:31], v[16:19], v[130:133], 0
	s_addc_u32 s21, s21, 0
	s_mulk_i32 s39, 0xc0
	v_lshl_add_u64 v[210:211], v[82:83], 1, s[20:21]
	v_lshl_add_u64 v[212:213], v[84:85], 1, s[20:21]
	s_add_u32 s20, s49, s39
	s_addc_u32 s21, s48, 0
	s_add_u32 s20, s20, 0x10030000
	v_mfma_f32_32x32x16_bf16 v[0:15], v[32:35], v[134:137], v[0:15]
	s_addc_u32 s21, s21, 0
	v_ashrrev_i32_e32 v209, 31, v208
	v_ashrrev_i32_e32 v207, 31, v206
	v_lshl_add_u64 v[214:215], v[76:77], 1, s[20:21]
	v_lshl_add_u64 v[216:217], v[78:79], 1, s[20:21]
	s_movk_i32 s20, 0xff01
	v_mfma_f32_32x32x16_bf16 v[16:31], v[38:41], v[134:137], v[16:31]
	ds_read_b128 v[32:35], v37 offset:64
	ds_read_b128 v[38:41], v37 offset:96
	s_waitcnt lgkmcnt(0)
	v_mfma_f32_32x32x16_bf16 v[0:15], v[32:35], v[138:141], v[0:15]
	ds_read_b128 v[32:35], v37 offset:6720
	ds_read_b128 v[42:45], v37 offset:6752
	s_waitcnt lgkmcnt(0)
	v_mfma_f32_32x32x16_bf16 v[16:31], v[32:35], v[138:141], v[16:31]
	v_mfma_f32_32x32x16_bf16 v[0:15], v[38:41], v[142:145], v[0:15]
	ds_read_b128 v[32:35], v37 offset:128
	ds_read_b128 v[38:41], v37 offset:160
	v_mfma_f32_32x32x16_bf16 v[16:31], v[42:45], v[142:145], v[16:31]
	s_waitcnt lgkmcnt(0)
	v_mfma_f32_32x32x16_bf16 v[0:15], v[32:35], v[146:149], v[0:15]
	ds_read_b128 v[32:35], v37 offset:6784
	ds_read_b128 v[42:45], v37 offset:6816
	s_waitcnt lgkmcnt(0)
	v_mfma_f32_32x32x16_bf16 v[16:31], v[32:35], v[146:149], v[16:31]
	v_mfma_f32_32x32x16_bf16 v[0:15], v[38:41], v[150:153], v[0:15]
	v_mfma_f32_32x32x16_bf16 v[16:31], v[42:45], v[150:153], v[16:31]
	s_nop 15
	s_nop 7
	s_nop 0
	v_max3_f32 v32, v0, v16, v1
	s_nop 0
	v_max3_f32 v32, v32, v17, v2
	s_nop 9
	v_max_f32_e32 v33, v31, v31
	v_max3_f32 v32, v32, v18, v3
	s_nop 0
	v_max3_f32 v32, v32, v19, v4
	s_nop 0
	v_max3_f32 v32, v32, v20, v5
	s_nop 0
	v_max3_f32 v32, v32, v21, v6
	s_nop 0
	v_max3_f32 v32, v32, v22, v7
	s_nop 0
	v_max3_f32 v32, v32, v23, v8
	s_nop 0
	v_max3_f32 v32, v32, v24, v9
	s_nop 0
	v_max3_f32 v32, v32, v25, v10
	s_nop 0
	v_max3_f32 v32, v32, v26, v11
	s_nop 0
	v_max3_f32 v32, v32, v27, v12
	s_nop 0
	v_max3_f32 v32, v32, v28, v13
	s_nop 0
	v_max3_f32 v32, v32, v29, v14
	s_nop 0
	v_max3_f32 v32, v32, v30, v15
	s_nop 0
	v_max_f32_e32 v32, v32, v32
	v_max_f32_e32 v32, v32, v33
	v_mov_b32_e32 v33, v32
	s_nop 1
	v_permlane32_swap_b32_e32 v32, v33
	v_max_f32_e32 v33, v33, v33
	v_max_f32_e32 v32, v32, v32
	v_max_f32_e32 v80, v32, v33
	v_sub_f32_e32 v16, v16, v80
	v_sub_f32_e32 v0, v0, v80
	v_sub_f32_e32 v17, v17, v80
	v_sub_f32_e32 v1, v1, v80
	v_exp_f32_e32 v37, v0
	v_exp_f32_e32 v38, v16
	v_sub_f32_e32 v32, v2, v80
	v_exp_f32_e32 v0, v1
	v_exp_f32_e32 v2, v17
	v_sub_f32_e32 v33, v3, v80
	v_add_f32_e32 v1, v37, v38
	v_mov_b32_e32 v3, v128
	v_sub_f32_e32 v18, v18, v80
	v_sub_f32_e32 v34, v4, v80
	v_sub_f32_e32 v35, v5, v80
	v_pk_add_f32 v[4:5], v[0:1], v[2:3]
	v_sub_f32_e32 v19, v19, v80
	v_pk_add_f32 v[4:5], v[4:5], v[4:5] op_sel_hi:[0,1]
	v_exp_f32_e32 v1, v32
	v_exp_f32_e32 v3, v18
	v_exp_f32_e32 v16, v33
	v_exp_f32_e32 v4, v19
	v_sub_f32_e32 v20, v20, v80
	v_add_f32_e32 v17, v1, v3
	v_sub_f32_e32 v21, v21, v80
	v_pk_add_f32 v[18:19], v[16:17], v[4:5]
	v_exp_f32_e32 v34, v34
	v_exp_f32_e32 v40, v20
	v_pk_add_f32 v[18:19], v[18:19], v[18:19] op_sel_hi:[0,1]
	v_sub_f32_e32 v39, v6, v80
	v_exp_f32_e32 v6, v35
	v_exp_f32_e32 v18, v21
	v_sub_f32_e32 v5, v7, v80
	v_add_f32_e32 v7, v34, v40
	v_sub_f32_e32 v22, v22, v80
	v_pk_add_f32 v[20:21], v[6:7], v[18:19]
	v_sub_f32_e32 v23, v23, v80
	v_exp_f32_e32 v17, v39
	v_pk_add_f32 v[20:21], v[20:21], v[20:21] op_sel_hi:[0,1]
	v_exp_f32_e32 v7, v22
	v_exp_f32_e32 v22, v5
	v_exp_f32_e32 v20, v23
	v_sub_f32_e32 v24, v24, v80
	v_add_f32_e32 v23, v17, v7
	v_sub_f32_e32 v5, v8, v80
	v_sub_f32_e32 v19, v9, v80
	v_pk_add_f32 v[8:9], v[22:23], v[20:21]
	v_sub_f32_e32 v25, v25, v80
	v_pk_add_f32 v[8:9], v[8:9], v[8:9] op_sel_hi:[0,1]
	v_exp_f32_e32 v5, v5
	v_exp_f32_e32 v21, v24
	v_exp_f32_e32 v24, v19
	v_exp_f32_e32 v8, v25
	v_sub_f32_e32 v26, v26, v80
	v_add_f32_e32 v25, v5, v21
	v_sub_f32_e32 v19, v10, v80
	v_sub_f32_e32 v23, v11, v80
	v_pk_add_f32 v[10:11], v[24:25], v[8:9]
	v_sub_f32_e32 v27, v27, v80
	v_pk_add_f32 v[10:11], v[10:11], v[10:11] op_sel_hi:[0,1]
	v_exp_f32_e32 v9, v19
	v_exp_f32_e32 v19, v26
	v_exp_f32_e32 v26, v23
	v_exp_f32_e32 v10, v27
	v_sub_f32_e32 v28, v28, v80
	v_add_f32_e32 v27, v9, v19
	v_sub_f32_e32 v23, v12, v80
	v_sub_f32_e32 v25, v13, v80
	v_pk_add_f32 v[12:13], v[26:27], v[10:11]
	v_sub_f32_e32 v29, v29, v80
	v_pk_add_f32 v[12:13], v[12:13], v[12:13] op_sel_hi:[0,1]
	v_exp_f32_e32 v11, v23
	v_exp_f32_e32 v23, v28
	v_exp_f32_e32 v28, v25
	v_exp_f32_e32 v12, v29
	v_sub_f32_e32 v25, v14, v80
	v_add_f32_e32 v29, v11, v23
	v_sub_f32_e32 v27, v15, v80
	v_pk_add_f32 v[14:15], v[28:29], v[12:13]
	v_sub_f32_e32 v30, v30, v80
	v_sub_f32_e32 v31, v31, v80
	v_pk_add_f32 v[86:87], v[14:15], v[14:15] op_sel_hi:[0,1]
	v_cvt_pk_bf16_f32 v32, v37, v0
	v_mov_b32_e32 v0, v194
	v_exp_f32_e32 v81, v25
	v_exp_f32_e32 v89, v30
	v_exp_f32_e32 v88, v27
	v_exp_f32_e32 v86, v31
	v_cvt_pk_bf16_f32 v33, v1, v16
	v_cvt_pk_bf16_f32 v34, v34, v6
	v_cvt_pk_bf16_f32 v35, v17, v22
	v_cvt_pk_bf16_f32 v68, v5, v24
	v_cvt_pk_bf16_f32 v69, v9, v26
	v_cvt_pk_bf16_f32 v70, v11, v28
	v_cvt_pk_bf16_f32 v71, v81, v88
	v_cvt_pk_bf16_f32 v72, v38, v2
	v_cvt_pk_bf16_f32 v73, v3, v4
	v_cvt_pk_bf16_f32 v74, v40, v18
	v_cvt_pk_bf16_f32 v75, v7, v20
	v_cvt_pk_bf16_f32 v64, v21, v8
	v_cvt_pk_bf16_f32 v65, v19, v10
	v_cvt_pk_bf16_f32 v66, v23, v12
	v_cvt_pk_bf16_f32 v67, v89, v86
	v_add_f32_e32 v89, v81, v89
	v_add_u32_e32 v37, 0, v0
	ds_read_b128 v[0:3], v37
	ds_read_b128 v[38:41], v37 offset:32
	s_waitcnt lgkmcnt(0)
; #define PG8_LAS __attribute__((address_space(3)))
; DEV void mla_unit(PG8_LAS unsigned char* lds, const bf16_t* Q, const bf16_t* K, const bf16_t* VT, bf16_t* O) {
;     ...
;         for (int sb = 0; sb < 2; ++sb) {
;             f32x16 p0, p1; int kfo_ = kfo; asm volatile("" : "+v"(kfo_));
; #pragma unroll
;             for (int d0 = 0; d0 < 6; ++d0) {
;                 const bf16x8 k0 = *(PG8_LAS const bf16x8*)(Kb + kfo_ + d0 * 32), k1 = *(PG8_LAS const bf16x8*)(Kb + kfo_ + 32 * 208 + d0 * 32);
;                 p0 = __builtin_amdgcn_mfma_f32_32x32x16_bf16(k0, qf[sb][d0], d0 == 0 ? negm[sb] : p0, 0, 0, 0);
;                 p1 = __builtin_amdgcn_mfma_f32_32x32x16_bf16(k1, qf[sb][d0], d0 == 0 ? negm[sb] : p1, 0, 0, 0);
;             }
;             asm volatile("s_nop 15\n\ts_nop 7" : "+v"(p0), "+v"(p1));
;             float mx = max3f(p0[0], p1[0], p0[1]);
; #pragma unroll
;             for (int r = 1; r < 15; ++r) mx = max3f(mx, p1[r], p0[r + 1]);
;             mx = hmax32(fmaxf(mx, p1[15]));
;             if (t == 0 || __any(mx > 8.f)) {
;                 const float dl = (t == 0) ? mx : fmaxf(mx, 0.f); mhat[sb] += dl;
; #pragma unroll
;                 for (int r = 0; r < 16; ++r) { p0[r] -= dl; p1[r] -= dl; negm[sb][r] = -mhat[sb]; }
;                 if (t != 0) { const float f = __builtin_amdgcn_exp2f(-dl); lrun[sb] *= f;
; #pragma unroll
;                     for (int r = 0; r < 16; ++r) { o[sb][0][r] *= f; o[sb][1][r] *= f; } }
;             }
;             float rsum = 0.f;
; #pragma unroll
;             for (int r = 0; r < 16; ++r) { p0[r] = __builtin_amdgcn_exp2f(p0[r]); p1[r] = __builtin_amdgcn_exp2f(p1[r]); rsum += p0[r] + p1[r]; }
;             lrun[sb] += rsum;
; #pragma unroll
;             for (int ks = 0; ks < 4; ++ks) { u32x4 w;
;                 if (ks < 2) { w.x = pk2(p0[8 * ks + 0], p0[8 * ks + 1]); w.y = pk2(p0[8 * ks + 2], p0[8 * ks + 3]); w.z = pk2(p0[8 * ks + 4], p0[8 * ks + 5]); w.w = pk2(p0[8 * ks + 6], p0[8 * ks + 7]); }
;                 else { const int k2 = ks - 2; w.x = pk2(p1[8 * k2 + 0], p1[8 * k2 + 1]); w.y = pk2(p1[8 * k2 + 2], p1[8 * k2 + 3]); w.z = pk2(p1[8 * k2 + 4], p1[8 * k2 + 5]); w.w = pk2(p1[8 * k2 + 6], p1[8 * k2 + 7]); }
;                 pb[sb][ks] = __builtin_bit_cast(bf16x8, w); }
;         }
; #pragma unroll
;         for (int db = 0; db < 2; ++db)
; #pragma unroll
;             for (int ks = 0; ks < 4; ++ks) {
	v_mfma_f32_32x32x16_bf16 v[0:15], v[0:3], v[154:157], 0
	ds_read_b128 v[16:19], v37 offset:6656
	ds_read_b128 v[42:45], v37 offset:6688
	s_waitcnt lgkmcnt(0)
	v_mfma_f32_32x32x16_bf16 v[16:31], v[16:19], v[154:157], 0
	v_mfma_f32_32x32x16_bf16 v[0:15], v[38:41], v[158:161], v[0:15]
	v_mfma_f32_32x32x16_bf16 v[16:31], v[42:45], v[158:161], v[16:31]
	ds_read_b128 v[38:41], v37 offset:64
	ds_read_b128 v[42:45], v37 offset:96
	s_waitcnt lgkmcnt(0)
	v_mfma_f32_32x32x16_bf16 v[0:15], v[38:41], v[162:165], v[0:15]
	ds_read_b128 v[38:41], v37 offset:6720
	ds_read_b128 v[46:49], v37 offset:6752
	s_waitcnt lgkmcnt(0)
	v_mfma_f32_32x32x16_bf16 v[16:31], v[38:41], v[162:165], v[16:31]
	v_mfma_f32_32x32x16_bf16 v[0:15], v[42:45], v[166:169], v[0:15]
	ds_read_b128 v[38:41], v37 offset:128
	ds_read_b128 v[42:45], v37 offset:160
	v_mfma_f32_32x32x16_bf16 v[16:31], v[46:49], v[166:169], v[16:31]
	s_waitcnt lgkmcnt(0)
	v_mfma_f32_32x32x16_bf16 v[0:15], v[38:41], v[170:173], v[0:15]
	ds_read_b128 v[38:41], v37 offset:6784
	ds_read_b128 v[46:49], v37 offset:6816
	s_waitcnt lgkmcnt(0)
	v_mfma_f32_32x32x16_bf16 v[16:31], v[38:41], v[170:173], v[16:31]
	v_mfma_f32_32x32x16_bf16 v[0:15], v[42:45], v[174:177], v[0:15]
	v_mfma_f32_32x32x16_bf16 v[16:31], v[46:49], v[174:177], v[16:31]
	s_nop 15
	s_nop 7
	s_nop 0
	v_max3_f32 v36, v0, v16, v1
	s_nop 0
	v_max3_f32 v36, v36, v17, v2
	s_nop 9
	v_max_f32_e32 v37, v31, v31
	v_max3_f32 v36, v36, v18, v3
	s_nop 0
	v_max3_f32 v36, v36, v19, v4
	s_nop 0
	v_max3_f32 v36, v36, v20, v5
	s_nop 0
	v_max3_f32 v36, v36, v21, v6
	s_nop 0
	v_max3_f32 v36, v36, v22, v7
	s_nop 0
	v_max3_f32 v36, v36, v23, v8
	s_nop 0
	v_max3_f32 v36, v36, v24, v9
	s_nop 0
	v_max3_f32 v36, v36, v25, v10
	s_nop 0
	v_max3_f32 v36, v36, v26, v11
	s_nop 0
	v_max3_f32 v36, v36, v27, v12
	s_nop 0
	v_max3_f32 v36, v36, v28, v13
	s_nop 0
	v_max3_f32 v36, v36, v29, v14
	s_nop 0
	v_max3_f32 v36, v36, v30, v15
	s_nop 0
	v_max_f32_e32 v36, v36, v36
	v_max_f32_e32 v36, v36, v37
	v_mov_b32_e32 v37, v36
	s_nop 1
	v_permlane32_swap_b32_e32 v36, v37
	v_max_f32_e32 v37, v37, v37
	v_max_f32_e32 v36, v36, v36
	v_max_f32_e32 v106, v36, v37
	v_sub_f32_e32 v16, v16, v106
	v_sub_f32_e32 v0, v0, v106
	v_sub_f32_e32 v17, v17, v106
	v_sub_f32_e32 v1, v1, v106
	v_exp_f32_e32 v39, v0
	v_exp_f32_e32 v40, v16
	v_exp_f32_e32 v0, v1
	v_exp_f32_e32 v16, v17
	v_mov_b32_e32 v17, v128
	v_add_f32_e32 v1, v39, v40
	v_sub_f32_e32 v36, v18, v106
	v_sub_f32_e32 v38, v2, v106
	v_sub_f32_e32 v41, v3, v106
	v_pk_add_f32 v[2:3], v[0:1], v[16:17]
	v_sub_f32_e32 v37, v19, v106
	v_pk_add_f32 v[18:19], v[2:3], v[2:3] op_sel_hi:[0,1]
	v_exp_f32_e32 v1, v38
	v_exp_f32_e32 v17, v36
	v_exp_f32_e32 v2, v41
	v_exp_f32_e32 v18, v37
	v_sub_f32_e32 v20, v20, v106
	v_add_f32_e32 v3, v1, v17
	v_sub_f32_e32 v36, v4, v106
	v_sub_f32_e32 v37, v5, v106
	v_pk_add_f32 v[4:5], v[2:3], v[18:19]
	v_sub_f32_e32 v21, v21, v106
	v_pk_add_f32 v[4:5], v[4:5], v[4:5] op_sel_hi:[0,1]
	v_exp_f32_e32 v3, v36
	v_exp_f32_e32 v19, v20
	v_exp_f32_e32 v20, v37
	v_exp_f32_e32 v4, v21
	v_sub_f32_e32 v22, v22, v106
	v_add_f32_e32 v21, v3, v19
	v_sub_f32_e32 v36, v6, v106
	v_sub_f32_e32 v37, v7, v106
	v_pk_add_f32 v[6:7], v[20:21], v[4:5]
	v_sub_f32_e32 v23, v23, v106
	v_pk_add_f32 v[6:7], v[6:7], v[6:7] op_sel_hi:[0,1]
	v_exp_f32_e32 v5, v36
	v_exp_f32_e32 v21, v22
	v_exp_f32_e32 v22, v37
	v_exp_f32_e32 v6, v23
	v_sub_f32_e32 v24, v24, v106
	v_add_f32_e32 v23, v5, v21
	v_sub_f32_e32 v36, v8, v106
	v_sub_f32_e32 v37, v9, v106
	v_pk_add_f32 v[8:9], v[22:23], v[6:7]
	v_sub_f32_e32 v25, v25, v106
	v_pk_add_f32 v[8:9], v[8:9], v[8:9] op_sel_hi:[0,1]
	v_exp_f32_e32 v7, v36
	v_exp_f32_e32 v23, v24
	v_exp_f32_e32 v24, v37
	v_exp_f32_e32 v8, v25
	v_sub_f32_e32 v26, v26, v106
	v_add_f32_e32 v25, v7, v23
	v_sub_f32_e32 v36, v10, v106
	v_sub_f32_e32 v37, v11, v106
	v_pk_add_f32 v[10:11], v[24:25], v[8:9]
	v_sub_f32_e32 v27, v27, v106
	v_pk_add_f32 v[10:11], v[10:11], v[10:11] op_sel_hi:[0,1]
	v_exp_f32_e32 v9, v36
	v_exp_f32_e32 v25, v26
	v_exp_f32_e32 v26, v37
	v_exp_f32_e32 v10, v27
	v_sub_f32_e32 v28, v28, v106
	v_add_f32_e32 v27, v9, v25
	v_sub_f32_e32 v36, v12, v106
	v_sub_f32_e32 v37, v13, v106
	v_pk_add_f32 v[12:13], v[26:27], v[10:11]
	v_sub_f32_e32 v29, v29, v106
	v_pk_add_f32 v[12:13], v[12:13], v[12:13] op_sel_hi:[0,1]
	v_exp_f32_e32 v11, v36
	v_exp_f32_e32 v27, v28
	v_exp_f32_e32 v28, v37
	v_exp_f32_e32 v12, v29
	v_sub_f32_e32 v36, v14, v106
	v_add_f32_e32 v29, v11, v27
	v_sub_f32_e32 v37, v15, v106
	v_pk_add_f32 v[14:15], v[28:29], v[12:13]
	v_sub_f32_e32 v30, v30, v106
	v_sub_f32_e32 v31, v31, v106
	v_pk_add_f32 v[108:109], v[14:15], v[14:15] op_sel_hi:[0,1]
	v_exp_f32_e32 v107, v36
	v_exp_f32_e32 v111, v30
	v_exp_f32_e32 v110, v37
	v_exp_f32_e32 v108, v31
	v_cvt_pk_bf16_f32 v0, v39, v0
	v_cvt_pk_bf16_f32 v1, v1, v2
	v_cvt_pk_bf16_f32 v2, v3, v20
	v_cvt_pk_bf16_f32 v3, v5, v22
	v_cvt_pk_bf16_f32 v90, v7, v24
	v_cvt_pk_bf16_f32 v91, v9, v26
	v_cvt_pk_bf16_f32 v92, v11, v28
	v_cvt_pk_bf16_f32 v93, v107, v110
	v_cvt_pk_bf16_f32 v94, v40, v16
	v_cvt_pk_bf16_f32 v95, v17, v18
	v_cvt_pk_bf16_f32 v96, v19, v4
	v_cvt_pk_bf16_f32 v97, v21, v6
	v_cvt_pk_bf16_f32 v98, v23, v8
	v_cvt_pk_bf16_f32 v99, v25, v10
	v_cvt_pk_bf16_f32 v100, v27, v12
	v_cvt_pk_bf16_f32 v101, v111, v108
	ds_read_b128 v[4:7], v112 offset:13312
	ds_read_b128 v[8:11], v112 offset:13344
	s_waitcnt lgkmcnt(0)
	v_mfma_f32_32x32x16_bf16 v[48:63], v[4:7], v[32:35], 0
	ds_read_b128 v[102:105], v112 offset:17952
	v_add_f32_e32 v111, v107, v111
	v_mfma_f32_32x32x16_bf16 v[16:31], v[4:7], v[0:3], 0
	ds_read_b128 v[4:7], v112 offset:13376
	v_mfma_f32_32x32x16_bf16 v[48:63], v[8:11], v[68:71], v[48:63]
	v_mfma_f32_32x32x16_bf16 v[16:31], v[8:11], v[90:93], v[16:31]
	s_waitcnt lgkmcnt(0)
	v_mfma_f32_32x32x16_bf16 v[48:63], v[4:7], v[72:75], v[48:63]
	v_mfma_f32_32x32x16_bf16 v[16:31], v[4:7], v[94:97], v[16:31]
	ds_read_b128 v[4:7], v112 offset:13408
	s_waitcnt lgkmcnt(0)
	v_mfma_f32_32x32x16_bf16 v[48:63], v[4:7], v[64:67], v[48:63]
	v_mfma_f32_32x32x16_bf16 v[16:31], v[4:7], v[98:101], v[16:31]
	ds_read_b128 v[4:7], v112 offset:17920
	s_waitcnt lgkmcnt(0)
	v_mfma_f32_32x32x16_bf16 v[32:47], v[4:7], v[32:35], 0
	v_mfma_f32_32x32x16_bf16 v[0:15], v[4:7], v[0:3], 0
	v_mfma_f32_32x32x16_bf16 v[32:47], v[102:105], v[68:71], v[32:47]
	ds_read_b128 v[68:71], v112 offset:17984
	v_mfma_f32_32x32x16_bf16 v[0:15], v[102:105], v[90:93], v[0:15]
	s_waitcnt lgkmcnt(0)
	v_mfma_f32_32x32x16_bf16 v[32:47], v[68:71], v[72:75], v[32:47]
	ds_read_b128 v[72:75], v112 offset:18016
	s_waitcnt vmcnt(0) lgkmcnt(0)
	s_barrier
; #define PG8_LAS __attribute__((address_space(3)))
; DEV float max3f(float a, float b, float c) { float r; asm("v_max3_f32 %0, %1, %2, %3" : "=v"(r) : "v"(a), "v"(b), "v"(c)); return r; }
; DEV float hmax32(float x) { auto rr = __builtin_amdgcn_permlane32_swap(__float_as_uint(x), __float_as_uint(x), false, false); return fmaxf(__uint_as_float(rr[0]), __uint_as_float(rr[1])); }
; DEV void mla_unit(PG8_LAS unsigned char* lds, const bf16_t* Q, const bf16_t* K, const bf16_t* VT, bf16_t* O) {
;     ...
;     for (int t = 0; t < NT; ++t) {
;         const int cur = t & 1;
;         if (t + 1 < NT) MLA_DMA((t + 1) * 64, cur ^ 1);
;         PG8_LAS const unsigned char* Kb = lds + cur * BUFB;
;         bf16x8 pb[2][4];
; #pragma unroll
;         for (int sb = 0; sb < 2; ++sb) {
;             f32x16 p0, p1; int kfo_ = kfo; asm volatile("" : "+v"(kfo_));
; #pragma unroll
;             for (int d0 = 0; d0 < 6; ++d0) {
;                 const bf16x8 k0 = *(PG8_LAS const bf16x8*)(Kb + kfo_ + d0 * 32), k1 = *(PG8_LAS const bf16x8*)(Kb + kfo_ + 32 * 208 + d0 * 32);
;                 p0 = __builtin_amdgcn_mfma_f32_32x32x16_bf16(k0, qf[sb][d0], d0 == 0 ? negm[sb] : p0, 0, 0, 0);
;                 p1 = __builtin_amdgcn_mfma_f32_32x32x16_bf16(k1, qf[sb][d0], d0 == 0 ? negm[sb] : p1, 0, 0, 0);
;             }
;             asm volatile("s_nop 15\n\ts_nop 7" : "+v"(p0), "+v"(p1));
;             float mx = max3f(p0[0], p1[0], p0[1]);
; #pragma unroll
;             for (int r = 1; r < 15; ++r) mx = max3f(mx, p1[r], p0[r + 1]);
;             mx = hmax32(fmaxf(mx, p1[15]));
;             if (t == 0 || __any(mx > 8.f)) {
;                 const float dl = (t == 0) ? mx : fmaxf(mx, 0.f); mhat[sb] += dl;
; #pragma unroll
;                 for (int r = 0; r < 16; ++r) { p0[r] -= dl; p1[r] -= dl; negm[sb][r] = -mhat[sb]; }
	v_mfma_f32_32x32x16_bf16 v[0:15], v[68:71], v[94:97], v[0:15]
	v_add_f32_e64 v68, v88, v86
	v_add_f32_e64 v69, v89, v87
	v_pk_add_f32 v[68:69], v[68:69], v[68:69] op_sel_hi:[0,1]
	v_mov_b32_e32 v81, v69
	v_pk_add_f32 v[218:219], v[80:81], 0 op_sel_hi:[1,0]
	v_mfma_f32_32x32x16_bf16 v[32:47], v[72:75], v[64:67], v[32:47]
	v_add_f32_e64 v66, v110, v108
	v_add_f32_e64 v67, v111, v109
	v_add_f32_e64 v64, -v218, neg(0)
	v_add_f32_e64 v65, -v219, neg(0)
	v_pk_add_f32 v[66:67], v[66:67], v[66:67] op_sel_hi:[0,1]
	v_mov_b32_e32 v107, v67
	v_pk_add_f32 v[220:221], v[106:107], 0 op_sel_hi:[1,0]
	v_mov_b32_e32 v65, v64
	v_pk_add_f32 v[80:81], v[220:221], 0 neg_lo:[1,1] neg_hi:[1,1]
	v_mfma_f32_32x32x16_bf16 v[0:15], v[72:75], v[98:101], v[0:15]
	v_mov_b32_e32 v81, v80
	v_mov_b32_e32 v82, v80
	v_mov_b32_e32 v83, v80
	v_mov_b32_e32 v84, v80
	v_mov_b32_e32 v85, v80
	v_mov_b32_e32 v86, v80
	v_mov_b32_e32 v87, v80
	v_mov_b32_e32 v88, v80
	v_mov_b32_e32 v89, v80
	v_mov_b32_e32 v90, v80
	v_mov_b32_e32 v91, v80
	v_mov_b32_e32 v92, v80
	v_mov_b32_e32 v93, v80
	v_mov_b32_e32 v94, v80
	v_mov_b32_e32 v95, v80
	v_mov_b32_e32 v66, v64
	v_mov_b32_e32 v67, v64
	v_mov_b32_e32 v68, v64
	v_mov_b32_e32 v69, v64
	v_mov_b32_e32 v70, v64
	v_mov_b32_e32 v71, v64
	v_mov_b32_e32 v72, v64
	v_mov_b32_e32 v73, v64
	v_mov_b32_e32 v74, v64
	v_mov_b32_e32 v75, v64
	v_mov_b32_e32 v76, v64
	v_mov_b32_e32 v77, v64
	v_mov_b32_e32 v78, v64
	v_mov_b32_e32 v79, v64
	s_mov_b32 s21, 0x5800
	v_add_u32_e32 v222, s21, v194
	ds_read_b128 v[186:189], v222
	ds_read_b128 v[190:193], v222 offset:6656
	ds_read_b128 v[238:241], v222 offset:32
	ds_read_b128 v[242:245], v222 offset:6688
.Lmla_top:
	s_xor_b32 s22, s21, 0x5800
	s_cmp_lg_u32 s20, -1
	s_cselect_b32 s23, 1, 0
	ds_read_b128 v[178:181], v222 offset:64
	ds_read_b128 v[182:185], v222 offset:6720
	ds_read_b128 v[230:233], v222 offset:96
	ds_read_b128 v[234:237], v222 offset:6752
	ds_read_b128 v[196:199], v222 offset:128
	ds_read_b128 v[200:203], v222 offset:6784
	ds_read_b128 v[246:249], v222 offset:160
	ds_read_b128 v[250:253], v222 offset:6816
	s_waitcnt lgkmcnt(10)
	v_mfma_f32_32x32x16_bf16 v[96:111], v[186:189], v[130:133], v[64:79]
	v_mfma_f32_32x32x16_bf16 v[112:127], v[190:193], v[130:133], v[64:79]
	s_cmp_eq_u32 s23, 0
	s_cbranch_scc1 .Lmla_dp0
	s_and_b64 vcc, exec, s[6:7]
	s_cbranch_vccnz .Lmla_dp0
	s_add_i32 m0, s22, s5
	v_lshl_add_u64 v[204:205], s[14:15], 0, v[214:215]
	global_load_lds_dwordx4 v[204:205], off
.Lmla_dp0:
	s_waitcnt lgkmcnt(8)
	v_mfma_f32_32x32x16_bf16 v[96:111], v[238:241], v[134:137], v[96:111]
	v_mfma_f32_32x32x16_bf16 v[112:127], v[242:245], v[134:137], v[112:127]
	s_cmp_eq_u32 s23, 0
	s_cbranch_scc1 .Lmla_dp1
	s_and_b64 vcc, exec, s[8:9]
	s_cbranch_vccnz .Lmla_dp1
	s_add_i32 m0, s22, s4
	v_lshl_add_u64 v[204:205], s[14:15], 0, v[216:217]
	global_load_lds_dwordx4 v[204:205], off
.Lmla_dp1:
	s_waitcnt lgkmcnt(6)
	v_mfma_f32_32x32x16_bf16 v[96:111], v[178:181], v[138:141], v[96:111]
	v_mfma_f32_32x32x16_bf16 v[112:127], v[182:185], v[138:141], v[112:127]
	s_cmp_eq_u32 s23, 0
	s_cbranch_scc1 .Lmla_dp2
	s_and_b64 vcc, exec, s[10:11]
	s_cbranch_vccnz .Lmla_dp2
	s_add_i32 m0, s22, s5
	s_add_i32 m0, m0, 0x3400
	v_lshl_add_u64 v[204:205], s[14:15], 0, v[210:211]
	global_load_lds_dwordx4 v[204:205], off
.Lmla_dp2:
	s_waitcnt lgkmcnt(4)
	v_mfma_f32_32x32x16_bf16 v[96:111], v[230:233], v[142:145], v[96:111]
	v_mfma_f32_32x32x16_bf16 v[112:127], v[234:237], v[142:145], v[112:127]
	s_cmp_eq_u32 s23, 0
	s_cbranch_scc1 .Lmla_dp3
	s_andn2_b64 vcc, exec, s[16:17]
	s_cbranch_vccnz .Lmla_dp3
	s_add_i32 m0, s22, s4
	s_add_i32 m0, m0, 0x3400
	v_lshl_add_u64 v[204:205], s[14:15], 0, v[212:213]
	global_load_lds_dwordx4 v[204:205], off
.Lmla_dp3:
	s_waitcnt lgkmcnt(2)
	v_mfma_f32_32x32x16_bf16 v[96:111], v[196:199], v[146:149], v[96:111]
	v_mfma_f32_32x32x16_bf16 v[112:127], v[200:203], v[146:149], v[112:127]
	s_waitcnt lgkmcnt(0)
	v_mfma_f32_32x32x16_bf16 v[96:111], v[246:249], v[150:153], v[96:111]
	v_mfma_f32_32x32x16_bf16 v[112:127], v[250:253], v[150:153], v[112:127]
	v_mfma_f32_32x32x16_bf16 v[178:193], v[196:199], v[170:173], v[80:95]
	ds_read_b128 v[196:199], v222
	v_mfma_f32_32x32x16_bf16 v[230:245], v[200:203], v[170:173], v[80:95]
	ds_read_b128 v[200:203], v222 offset:6656
	s_nop 8
	v_max3_f32 v225, v96, v112, v97
	v_max3_f32 v229, v104, v120, v105
	v_max3_f32 v225, v225, v113, v98
	v_max3_f32 v229, v229, v121, v106
	v_max3_f32 v225, v225, v114, v99
	v_max3_f32 v229, v229, v122, v107
	v_mfma_f32_32x32x16_bf16 v[178:193], v[246:249], v[174:177], v[178:193]
	ds_read_b128 v[246:249], v222 offset:32
	v_max3_f32 v225, v225, v115, v100
	v_max3_f32 v229, v229, v123, v108
	v_max3_f32 v225, v225, v116, v101
	v_max3_f32 v229, v229, v124, v109
	v_max3_f32 v225, v225, v117, v102
	v_max3_f32 v229, v229, v125, v110
	v_mfma_f32_32x32x16_bf16 v[230:245], v[250:253], v[174:177], v[230:245]
	ds_read_b128 v[250:253], v222 offset:6688
	v_max3_f32 v225, v225, v118, v103
	v_max3_f32 v229, v229, v126, v111
	v_max3_f32 v225, v225, v119, v127
	v_max_f32_e32 v225, v225, v229
	v_mov_b32_e32 v229, v225
	s_nop 1
	v_permlane32_swap_b32_e32 v225, v229
	v_max_f32_e32 v225, v225, v229
	v_cmp_lt_f32_e32 vcc, s69, v225
	s_cbranch_vccnz .Lmla_resc0
; #define PG8_LAS __attribute__((address_space(3)))
; DEV unsigned pk2(float lo, float hi) { return pg8::cvt_pk_bf16(lo, hi); }
; DEV float max3f(float a, float b, float c) { float r; asm("v_max3_f32 %0, %1, %2, %3" : "=v"(r) : "v"(a), "v"(b), "v"(c)); return r; }
; DEV void mla_unit(PG8_LAS unsigned char* lds, const bf16_t* Q, const bf16_t* K, const bf16_t* VT, bf16_t* O) {
;     ...
;             float mx = max3f(p0[0], p1[0], p0[1]);
; #pragma unroll
;             for (int r = 1; r < 15; ++r) mx = max3f(mx, p1[r], p0[r + 1]);
;             mx = hmax32(fmaxf(mx, p1[15]));
;             if (t == 0 || __any(mx > 8.f)) {
;                 const float dl = (t == 0) ? mx : fmaxf(mx, 0.f); mhat[sb] += dl;
; #pragma unroll
;                 for (int r = 0; r < 16; ++r) { p0[r] -= dl; p1[r] -= dl; negm[sb][r] = -mhat[sb]; }
;                 if (t != 0) { const float f = __builtin_amdgcn_exp2f(-dl); lrun[sb] *= f;
; #pragma unroll
;                     for (int r = 0; r < 16; ++r) { o[sb][0][r] *= f; o[sb][1][r] *= f; } }
;             }
;             float rsum = 0.f;
; #pragma unroll
;             for (int r = 0; r < 16; ++r) { p0[r] = __builtin_amdgcn_exp2f(p0[r]); p1[r] = __builtin_amdgcn_exp2f(p1[r]); rsum += p0[r] + p1[r]; }
;             lrun[sb] += rsum;
; #pragma unroll
;             for (int ks = 0; ks < 4; ++ks) { u32x4 w;
;                 if (ks < 2) { w.x = pk2(p0[8 * ks + 0], p0[8 * ks + 1]); w.y = pk2(p0[8 * ks + 2], p0[8 * ks + 3]); w.z = pk2(p0[8 * ks + 4], p0[8 * ks + 5]); w.w = pk2(p0[8 * ks + 6], p0[8 * ks + 7]); }
;                 else { const int k2 = ks - 2; w.x = pk2(p1[8 * k2 + 0], p1[8 * k2 + 1]); w.y = pk2(p1[8 * k2 + 2], p1[8 * k2 + 3]); w.z = pk2(p1[8 * k2 + 4], p1[8 * k2 + 5]); w.w = pk2(p1[8 * k2 + 6], p1[8 * k2 + 7]); }
;                 pb[sb][ks] = __builtin_bit_cast(bf16x8, w); }
;         }
; #pragma unroll
;         for (int db = 0; db < 2; ++db)
; #pragma unroll
;             for (int ks = 0; ks < 4; ++ks) {
;                 const bf16x8 vf = *(PG8_LAS const bf16x8*)(Kb + vfo + db * 32 * 144 + ks * 32);
;                 o[0][db] = __builtin_amdgcn_mfma_f32_32x32x16_bf16(vf, pb[0][ks], o[0][db], 0, 0, 0);
;                 o[1][db] = __builtin_amdgcn_mfma_f32_32x32x16_bf16(vf, pb[1][ks], o[1][db], 0, 0, 0);
.Lmla_back0:
	v_exp_f32_e32 v96, v96
	v_exp_f32_e32 v97, v97
	v_exp_f32_e32 v98, v98
	v_add_f32_e32 v225, v96, v97
	v_cvt_pk_bf16_f32 v96, v96, v97
	v_exp_f32_e32 v99, v99
	v_exp_f32_e32 v100, v100
	v_add_f32_e32 v229, v98, v99
	v_cvt_pk_bf16_f32 v97, v98, v99
	s_waitcnt lgkmcnt(3)
	v_mfma_f32_32x32x16_bf16 v[178:193], v[196:199], v[154:157], v[178:193]
	ds_read_b128 v[196:199], v222 offset:64
	v_exp_f32_e32 v101, v101
	v_exp_f32_e32 v102, v102
	v_add_f32_e32 v204, v100, v101
	v_cvt_pk_bf16_f32 v98, v100, v101
	v_exp_f32_e32 v103, v103
	v_exp_f32_e32 v104, v104
	v_add_f32_e32 v205, v102, v103
	v_cvt_pk_bf16_f32 v99, v102, v103
	v_exp_f32_e32 v105, v105
	s_waitcnt lgkmcnt(3)
	v_mfma_f32_32x32x16_bf16 v[230:245], v[200:203], v[154:157], v[230:245]
	ds_read_b128 v[200:203], v222 offset:6720
	v_add_f32_e32 v225, v225, v104
	v_exp_f32_e32 v106, v106
	v_add_f32_e32 v229, v229, v105
	v_cvt_pk_bf16_f32 v100, v104, v105
	v_exp_f32_e32 v107, v107
	v_add_f32_e32 v204, v204, v106
	v_exp_f32_e32 v108, v108
	v_add_f32_e32 v205, v205, v107
	v_cvt_pk_bf16_f32 v101, v106, v107
	s_waitcnt lgkmcnt(3)
	v_mfma_f32_32x32x16_bf16 v[178:193], v[246:249], v[158:161], v[178:193]
	ds_read_b128 v[246:249], v222 offset:96
	v_exp_f32_e32 v109, v109
	v_add_f32_e32 v225, v225, v108
	v_exp_f32_e32 v110, v110
	v_add_f32_e32 v229, v229, v109
	v_cvt_pk_bf16_f32 v102, v108, v109
	v_exp_f32_e32 v111, v111
	v_add_f32_e32 v204, v204, v110
	v_exp_f32_e32 v112, v112
	v_add_f32_e32 v205, v205, v111
	s_waitcnt lgkmcnt(3)
	v_mfma_f32_32x32x16_bf16 v[230:245], v[250:253], v[158:161], v[230:245]
	ds_read_b128 v[250:253], v222 offset:6752
	v_cvt_pk_bf16_f32 v103, v110, v111
	v_exp_f32_e32 v113, v113
	v_add_f32_e32 v225, v225, v112
	v_exp_f32_e32 v114, v114
	v_add_f32_e32 v229, v229, v113
	v_cvt_pk_bf16_f32 v112, v112, v113
	v_exp_f32_e32 v115, v115
	v_add_f32_e32 v204, v204, v114
	v_exp_f32_e32 v116, v116
	s_waitcnt lgkmcnt(3)
	v_mfma_f32_32x32x16_bf16 v[178:193], v[196:199], v[162:165], v[178:193]
	v_add_f32_e32 v205, v205, v115
	v_cvt_pk_bf16_f32 v113, v114, v115
	v_exp_f32_e32 v117, v117
	v_add_f32_e32 v225, v225, v116
	v_exp_f32_e32 v118, v118
	v_add_f32_e32 v229, v229, v117
	v_cvt_pk_bf16_f32 v114, v116, v117
	v_exp_f32_e32 v119, v119
	v_add_f32_e32 v204, v204, v118
	s_waitcnt lgkmcnt(2)
	v_mfma_f32_32x32x16_bf16 v[230:245], v[200:203], v[162:165], v[230:245]
	v_exp_f32_e32 v120, v120
	v_add_f32_e32 v205, v205, v119
	v_cvt_pk_bf16_f32 v115, v118, v119
	v_exp_f32_e32 v121, v121
	v_add_f32_e32 v225, v225, v120
	v_exp_f32_e32 v122, v122
	v_add_f32_e32 v229, v229, v121
	v_cvt_pk_bf16_f32 v116, v120, v121
	v_exp_f32_e32 v123, v123
	s_waitcnt lgkmcnt(1)
	v_mfma_f32_32x32x16_bf16 v[178:193], v[246:249], v[166:169], v[178:193]
	v_add_f32_e32 v204, v204, v122
	v_exp_f32_e32 v124, v124
	v_add_f32_e32 v205, v205, v123
	v_cvt_pk_bf16_f32 v117, v122, v123
	v_exp_f32_e32 v125, v125
	v_add_f32_e32 v225, v225, v124
	v_exp_f32_e32 v126, v126
	v_add_f32_e32 v229, v229, v125
	v_cvt_pk_bf16_f32 v118, v124, v125
	s_waitcnt lgkmcnt(0)
	v_mfma_f32_32x32x16_bf16 v[230:245], v[250:253], v[166:169], v[230:245]
	v_exp_f32_e32 v127, v127
	v_add_f32_e32 v204, v204, v126
	s_nop 0
	v_add_f32_e32 v205, v205, v127
	v_cvt_pk_bf16_f32 v119, v126, v127
	v_add_f32_e32 v225, v225, v229
	v_add_f32_e32 v204, v204, v205
	v_add_f32_e32 v225, v225, v204
	v_add_f32_e32 v219, v219, v225
	v_add_u32_e32 v223, s21, v195
	ds_read_b128 v[104:107], v223 offset:13312
	ds_read_b128 v[108:111], v223 offset:17920
	ds_read_b128 v[120:123], v223 offset:13344
	ds_read_b128 v[124:127], v223 offset:17952
	ds_read_b128 v[196:199], v223 offset:13376
	ds_read_b128 v[200:203], v223 offset:17984
	ds_read_b128 v[246:249], v223 offset:13408
	ds_read_b128 v[250:253], v223 offset:18016
	s_nop 3
	v_max3_f32 v225, v178, v230, v179
	v_max3_f32 v229, v186, v238, v187
	v_max3_f32 v225, v225, v231, v180
	v_max3_f32 v229, v229, v239, v188
	v_max3_f32 v225, v225, v232, v181
	v_max3_f32 v229, v229, v240, v189
	v_max3_f32 v225, v225, v233, v182
	v_max3_f32 v229, v229, v241, v190
	s_waitcnt lgkmcnt(7)
	v_mfma_f32_32x32x16_bf16 v[48:63], v[104:107], v[96:99], v[48:63]
	v_max3_f32 v225, v225, v234, v183
	v_max3_f32 v229, v229, v242, v191
	v_max3_f32 v225, v225, v235, v184
	v_max3_f32 v229, v229, v243, v192
	v_max3_f32 v225, v225, v236, v185
	v_max3_f32 v229, v229, v244, v193
	v_max3_f32 v225, v225, v237, v245
	v_max_f32_e32 v225, v225, v229
	s_waitcnt lgkmcnt(6)
	v_mfma_f32_32x32x16_bf16 v[32:47], v[108:111], v[96:99], v[32:47]
	v_mov_b32_e32 v229, v225
	s_nop 1
	v_permlane32_swap_b32_e32 v225, v229
	v_max_f32_e32 v225, v225, v229
	v_cmp_lt_f32_e32 vcc, s69, v225
	s_cbranch_vccnz .Lmla_resc1
; #define PG8_LAS __attribute__((address_space(3)))
; DEV unsigned pk2(float lo, float hi) { return pg8::cvt_pk_bf16(lo, hi); }
; DEV void mla_unit(PG8_LAS unsigned char* lds, const bf16_t* Q, const bf16_t* K, const bf16_t* VT, bf16_t* O) {
;     ...
;             float rsum = 0.f;
; #pragma unroll
;             for (int r = 0; r < 16; ++r) { p0[r] = __builtin_amdgcn_exp2f(p0[r]); p1[r] = __builtin_amdgcn_exp2f(p1[r]); rsum += p0[r] + p1[r]; }
;             lrun[sb] += rsum;
; #pragma unroll
;             for (int ks = 0; ks < 4; ++ks) { u32x4 w;
;                 if (ks < 2) { w.x = pk2(p0[8 * ks + 0], p0[8 * ks + 1]); w.y = pk2(p0[8 * ks + 2], p0[8 * ks + 3]); w.z = pk2(p0[8 * ks + 4], p0[8 * ks + 5]); w.w = pk2(p0[8 * ks + 6], p0[8 * ks + 7]); }
;                 else { const int k2 = ks - 2; w.x = pk2(p1[8 * k2 + 0], p1[8 * k2 + 1]); w.y = pk2(p1[8 * k2 + 2], p1[8 * k2 + 3]); w.z = pk2(p1[8 * k2 + 4], p1[8 * k2 + 5]); w.w = pk2(p1[8 * k2 + 6], p1[8 * k2 + 7]); }
;                 pb[sb][ks] = __builtin_bit_cast(bf16x8, w); }
;         }
; #pragma unroll
;         for (int db = 0; db < 2; ++db)
; #pragma unroll
;             for (int ks = 0; ks < 4; ++ks) {
;                 const bf16x8 vf = *(PG8_LAS const bf16x8*)(Kb + vfo + db * 32 * 144 + ks * 32);
;                 o[0][db] = __builtin_amdgcn_mfma_f32_32x32x16_bf16(vf, pb[0][ks], o[0][db], 0, 0, 0);
;                 o[1][db] = __builtin_amdgcn_mfma_f32_32x32x16_bf16(vf, pb[1][ks], o[1][db], 0, 0, 0);
;             }
;         __syncthreads();
.Lmla_back1:
	v_exp_f32_e32 v178, v178
	v_exp_f32_e32 v179, v179
	v_exp_f32_e32 v180, v180
	v_add_f32_e32 v225, v178, v179
	v_cvt_pk_bf16_f32 v178, v178, v179
	v_exp_f32_e32 v181, v181
	v_exp_f32_e32 v182, v182
	v_add_f32_e32 v229, v180, v181
	v_cvt_pk_bf16_f32 v179, v180, v181
	v_exp_f32_e32 v183, v183
	v_exp_f32_e32 v184, v184
	s_waitcnt lgkmcnt(5)
	v_mfma_f32_32x32x16_bf16 v[48:63], v[120:123], v[100:103], v[48:63]
	v_add_f32_e32 v204, v182, v183
	v_cvt_pk_bf16_f32 v180, v182, v183
	v_exp_f32_e32 v185, v185
	v_exp_f32_e32 v186, v186
	v_add_f32_e32 v205, v184, v185
	v_cvt_pk_bf16_f32 v181, v184, v185
	v_exp_f32_e32 v187, v187
	v_add_f32_e32 v225, v225, v186
	v_exp_f32_e32 v188, v188
	v_add_f32_e32 v229, v229, v187
	v_cvt_pk_bf16_f32 v182, v186, v187
	v_exp_f32_e32 v189, v189
	s_waitcnt lgkmcnt(4)
	v_mfma_f32_32x32x16_bf16 v[32:47], v[124:127], v[100:103], v[32:47]
	v_add_f32_e32 v204, v204, v188
	v_exp_f32_e32 v190, v190
	v_add_f32_e32 v205, v205, v189
	v_cvt_pk_bf16_f32 v183, v188, v189
	v_exp_f32_e32 v191, v191
	v_add_f32_e32 v225, v225, v190
	v_exp_f32_e32 v192, v192
	v_add_f32_e32 v229, v229, v191
	v_cvt_pk_bf16_f32 v184, v190, v191
	v_exp_f32_e32 v193, v193
	v_add_f32_e32 v204, v204, v192
	s_waitcnt lgkmcnt(3)
	v_mfma_f32_32x32x16_bf16 v[48:63], v[196:199], v[112:115], v[48:63]
	v_exp_f32_e32 v230, v230
	v_add_f32_e32 v205, v205, v193
	v_cvt_pk_bf16_f32 v185, v192, v193
	v_exp_f32_e32 v231, v231
	v_add_f32_e32 v225, v225, v230
	v_exp_f32_e32 v232, v232
	v_add_f32_e32 v229, v229, v231
	v_cvt_pk_bf16_f32 v230, v230, v231
	v_exp_f32_e32 v233, v233
	v_add_f32_e32 v204, v204, v232
	v_exp_f32_e32 v234, v234
	v_add_f32_e32 v205, v205, v233
	s_waitcnt lgkmcnt(2)
	v_mfma_f32_32x32x16_bf16 v[32:47], v[200:203], v[112:115], v[32:47]
	v_cvt_pk_bf16_f32 v231, v232, v233
	v_exp_f32_e32 v235, v235
	v_add_f32_e32 v225, v225, v234
	v_exp_f32_e32 v236, v236
	v_add_f32_e32 v229, v229, v235
	v_cvt_pk_bf16_f32 v232, v234, v235
	v_exp_f32_e32 v237, v237
	v_add_f32_e32 v204, v204, v236
	v_exp_f32_e32 v238, v238
	v_add_f32_e32 v205, v205, v237
	v_cvt_pk_bf16_f32 v233, v236, v237
	s_waitcnt lgkmcnt(1)
	v_mfma_f32_32x32x16_bf16 v[48:63], v[246:249], v[116:119], v[48:63]
	v_exp_f32_e32 v239, v239
	v_add_f32_e32 v225, v225, v238
	v_exp_f32_e32 v240, v240
	v_add_f32_e32 v229, v229, v239
	v_cvt_pk_bf16_f32 v234, v238, v239
	v_exp_f32_e32 v241, v241
	v_add_f32_e32 v204, v204, v240
	v_exp_f32_e32 v242, v242
	v_add_f32_e32 v205, v205, v241
	v_cvt_pk_bf16_f32 v235, v240, v241
	v_exp_f32_e32 v243, v243
	v_add_f32_e32 v225, v225, v242
	s_waitcnt lgkmcnt(0)
	v_mfma_f32_32x32x16_bf16 v[32:47], v[250:253], v[116:119], v[32:47]
	v_exp_f32_e32 v244, v244
	v_add_f32_e32 v229, v229, v243
	v_cvt_pk_bf16_f32 v236, v242, v243
	v_exp_f32_e32 v245, v245
	v_add_f32_e32 v204, v204, v244
	s_nop 0
	v_add_f32_e32 v205, v205, v245
	v_cvt_pk_bf16_f32 v237, v244, v245
	v_add_f32_e32 v225, v225, v229
	v_add_f32_e32 v204, v204, v205
	v_add_f32_e32 v225, v225, v204
	v_add_f32_e32 v221, v221, v225
	s_waitcnt vmcnt(0)
	s_barrier
	s_xor_b32 s21, s21, 0x5800
	v_add_u32_e32 v222, s21, v194
	v_mfma_f32_32x32x16_bf16 v[16:31], v[104:107], v[178:181], v[16:31]
	v_mfma_f32_32x32x16_bf16 v[0:15], v[108:111], v[178:181], v[0:15]
	ds_read_b128 v[186:189], v222
	ds_read_b128 v[190:193], v222 offset:6656
	ds_read_b128 v[238:241], v222 offset:32
	ds_read_b128 v[242:245], v222 offset:6688
	v_mfma_f32_32x32x16_bf16 v[16:31], v[120:123], v[182:185], v[16:31]
	v_mfma_f32_32x32x16_bf16 v[0:15], v[124:127], v[182:185], v[0:15]
	v_lshl_add_u64 v[210:211], v[210:211], 0, s[82:83]
	v_lshl_add_u64 v[212:213], v[212:213], 0, s[82:83]
	v_lshl_add_u64 v[214:215], v[214:215], 0, s[46:47]
	v_lshl_add_u64 v[216:217], v[216:217], 0, s[46:47]
	v_mfma_f32_32x32x16_bf16 v[16:31], v[196:199], v[230:233], v[16:31]
	v_mfma_f32_32x32x16_bf16 v[0:15], v[200:203], v[230:233], v[0:15]
	v_mfma_f32_32x32x16_bf16 v[16:31], v[246:249], v[234:237], v[16:31]
	v_mfma_f32_32x32x16_bf16 v[0:15], v[250:253], v[234:237], v[0:15]
	s_add_u32 s20, s20, 1
	s_cbranch_scc0 .Lmla_top
	s_waitcnt lgkmcnt(0)
	v_mov_b32_e32 v96, v221
	s_branch .LBB0_1227
; DEV void mla_unit(PG8_LAS unsigned char* lds, const bf16_t* Q, const bf16_t* K, const bf16_t* VT, bf16_t* O) {
;     ...
;             if (t == 0 || __any(mx > 8.f)) {
;                 const float dl = (t == 0) ? mx : fmaxf(mx, 0.f); mhat[sb] += dl;
; #pragma unroll
;                 for (int r = 0; r < 16; ++r) { p0[r] -= dl; p1[r] -= dl; negm[sb][r] = -mhat[sb]; }
;                 if (t != 0) { const float f = __builtin_amdgcn_exp2f(-dl); lrun[sb] *= f;
; #pragma unroll
;                     for (int r = 0; r < 16; ++r) { o[sb][0][r] *= f; o[sb][1][r] *= f; } }
;             }
.Lmla_resc0:
	v_max_f32_e32 v64, v225, v225
	v_max_f32_e32 v66, 0, v64
	v_pk_add_f32 v[112:113], v[112:113], v[66:67] op_sel_hi:[1,0] neg_lo:[0,1] neg_hi:[0,1]
	v_pk_add_f32 v[114:115], v[114:115], v[66:67] op_sel_hi:[1,0] neg_lo:[0,1] neg_hi:[0,1]
	v_pk_add_f32 v[116:117], v[116:117], v[66:67] op_sel_hi:[1,0] neg_lo:[0,1] neg_hi:[0,1]
	v_pk_add_f32 v[118:119], v[118:119], v[66:67] op_sel_hi:[1,0] neg_lo:[0,1] neg_hi:[0,1]
	v_pk_add_f32 v[120:121], v[120:121], v[66:67] op_sel_hi:[1,0] neg_lo:[0,1] neg_hi:[0,1]
	v_pk_add_f32 v[122:123], v[122:123], v[66:67] op_sel_hi:[1,0] neg_lo:[0,1] neg_hi:[0,1]
	v_pk_add_f32 v[124:125], v[124:125], v[66:67] op_sel_hi:[1,0] neg_lo:[0,1] neg_hi:[0,1]
	v_pk_add_f32 v[126:127], v[126:127], v[66:67] op_sel_hi:[1,0] neg_lo:[0,1] neg_hi:[0,1]
	v_pk_add_f32 v[96:97], v[96:97], v[66:67] op_sel_hi:[1,0] neg_lo:[0,1] neg_hi:[0,1]
	v_pk_add_f32 v[98:99], v[98:99], v[66:67] op_sel_hi:[1,0] neg_lo:[0,1] neg_hi:[0,1]
	v_pk_add_f32 v[100:101], v[100:101], v[66:67] op_sel_hi:[1,0] neg_lo:[0,1] neg_hi:[0,1]
	v_pk_add_f32 v[102:103], v[102:103], v[66:67] op_sel_hi:[1,0] neg_lo:[0,1] neg_hi:[0,1]
	v_pk_add_f32 v[104:105], v[104:105], v[66:67] op_sel_hi:[1,0] neg_lo:[0,1] neg_hi:[0,1]
	v_pk_add_f32 v[106:107], v[106:107], v[66:67] op_sel_hi:[1,0] neg_lo:[0,1] neg_hi:[0,1]
	v_pk_add_f32 v[108:109], v[108:109], v[66:67] op_sel_hi:[1,0] neg_lo:[0,1] neg_hi:[0,1]
	v_pk_add_f32 v[110:111], v[110:111], v[66:67] op_sel_hi:[1,0] neg_lo:[0,1] neg_hi:[0,1]
	v_exp_f32_e64 v67, -v66
	s_nop 0
	v_pk_add_f32 v[68:69], v[218:219], v[66:67]
	v_pk_mul_f32 v[64:65], v[218:219], v[66:67]
	v_mov_b32_e32 v66, v67
	v_mov_b32_e32 v69, v65
	v_pk_add_f32 v[64:65], v[68:69], 0 neg_lo:[1,1] neg_hi:[1,1]
	v_pk_mul_f32 v[62:63], v[62:63], v[66:67] op_sel_hi:[1,0]
	v_pk_mul_f32 v[60:61], v[60:61], v[66:67] op_sel_hi:[1,0]
	v_pk_mul_f32 v[58:59], v[58:59], v[66:67] op_sel_hi:[1,0]
	v_pk_mul_f32 v[56:57], v[56:57], v[66:67] op_sel_hi:[1,0]
	v_pk_mul_f32 v[54:55], v[54:55], v[66:67] op_sel_hi:[1,0]
	v_pk_mul_f32 v[52:53], v[52:53], v[66:67] op_sel_hi:[1,0]
	v_pk_mul_f32 v[50:51], v[50:51], v[66:67] op_sel_hi:[1,0]
	v_pk_mul_f32 v[48:49], v[48:49], v[66:67] op_sel_hi:[1,0]
	v_pk_mul_f32 v[46:47], v[46:47], v[66:67] op_sel_hi:[1,0]
	v_pk_mul_f32 v[44:45], v[44:45], v[66:67] op_sel_hi:[1,0]
	v_pk_mul_f32 v[42:43], v[42:43], v[66:67] op_sel_hi:[1,0]
	v_pk_mul_f32 v[40:41], v[40:41], v[66:67] op_sel_hi:[1,0]
	v_pk_mul_f32 v[38:39], v[38:39], v[66:67] op_sel_hi:[1,0]
	v_pk_mul_f32 v[36:37], v[36:37], v[66:67] op_sel_hi:[1,0]
	v_pk_mul_f32 v[34:35], v[34:35], v[66:67] op_sel_hi:[1,0]
	v_pk_mul_f32 v[32:33], v[32:33], v[66:67] op_sel_hi:[1,0]
	v_mov_b64_e32 v[218:219], v[68:69]
	v_mov_b32_e32 v65, v64
	v_mov_b32_e32 v66, v64
	v_mov_b32_e32 v67, v64
	v_mov_b32_e32 v68, v64
	v_mov_b32_e32 v69, v64
	v_mov_b32_e32 v70, v64
	v_mov_b32_e32 v71, v64
	v_mov_b32_e32 v72, v64
	v_mov_b32_e32 v73, v64
	v_mov_b32_e32 v74, v64
	v_mov_b32_e32 v75, v64
	v_mov_b32_e32 v76, v64
	v_mov_b32_e32 v77, v64
	v_mov_b32_e32 v78, v64
	v_mov_b32_e32 v79, v64
	s_branch .Lmla_back0
.Lmla_resc1:
	v_max_f32_e32 v80, v225, v225
	v_max_f32_e32 v82, 0, v80
	v_pk_add_f32 v[230:231], v[230:231], v[82:83] op_sel_hi:[1,0] neg_lo:[0,1] neg_hi:[0,1]
	v_pk_add_f32 v[232:233], v[232:233], v[82:83] op_sel_hi:[1,0] neg_lo:[0,1] neg_hi:[0,1]
	v_pk_add_f32 v[234:235], v[234:235], v[82:83] op_sel_hi:[1,0] neg_lo:[0,1] neg_hi:[0,1]
	v_pk_add_f32 v[236:237], v[236:237], v[82:83] op_sel_hi:[1,0] neg_lo:[0,1] neg_hi:[0,1]
	v_pk_add_f32 v[238:239], v[238:239], v[82:83] op_sel_hi:[1,0] neg_lo:[0,1] neg_hi:[0,1]
	v_pk_add_f32 v[240:241], v[240:241], v[82:83] op_sel_hi:[1,0] neg_lo:[0,1] neg_hi:[0,1]
	v_pk_add_f32 v[242:243], v[242:243], v[82:83] op_sel_hi:[1,0] neg_lo:[0,1] neg_hi:[0,1]
	v_pk_add_f32 v[244:245], v[244:245], v[82:83] op_sel_hi:[1,0] neg_lo:[0,1] neg_hi:[0,1]
	v_pk_add_f32 v[178:179], v[178:179], v[82:83] op_sel_hi:[1,0] neg_lo:[0,1] neg_hi:[0,1]
	v_pk_add_f32 v[180:181], v[180:181], v[82:83] op_sel_hi:[1,0] neg_lo:[0,1] neg_hi:[0,1]
	v_pk_add_f32 v[182:183], v[182:183], v[82:83] op_sel_hi:[1,0] neg_lo:[0,1] neg_hi:[0,1]
	v_pk_add_f32 v[184:185], v[184:185], v[82:83] op_sel_hi:[1,0] neg_lo:[0,1] neg_hi:[0,1]
	v_pk_add_f32 v[186:187], v[186:187], v[82:83] op_sel_hi:[1,0] neg_lo:[0,1] neg_hi:[0,1]
	v_pk_add_f32 v[188:189], v[188:189], v[82:83] op_sel_hi:[1,0] neg_lo:[0,1] neg_hi:[0,1]
	v_pk_add_f32 v[190:191], v[190:191], v[82:83] op_sel_hi:[1,0] neg_lo:[0,1] neg_hi:[0,1]
	v_pk_add_f32 v[192:193], v[192:193], v[82:83] op_sel_hi:[1,0] neg_lo:[0,1] neg_hi:[0,1]
	v_exp_f32_e64 v83, -v82
	s_nop 0
	v_pk_add_f32 v[84:85], v[220:221], v[82:83]
	v_pk_mul_f32 v[80:81], v[220:221], v[82:83]
	v_mov_b32_e32 v82, v83
	v_mov_b32_e32 v85, v81
	v_pk_add_f32 v[80:81], v[84:85], 0 neg_lo:[1,1] neg_hi:[1,1]
	v_pk_mul_f32 v[30:31], v[30:31], v[82:83] op_sel_hi:[1,0]
	v_pk_mul_f32 v[28:29], v[28:29], v[82:83] op_sel_hi:[1,0]
	v_pk_mul_f32 v[26:27], v[26:27], v[82:83] op_sel_hi:[1,0]
	v_pk_mul_f32 v[24:25], v[24:25], v[82:83] op_sel_hi:[1,0]
	v_pk_mul_f32 v[22:23], v[22:23], v[82:83] op_sel_hi:[1,0]
	v_pk_mul_f32 v[20:21], v[20:21], v[82:83] op_sel_hi:[1,0]
	v_pk_mul_f32 v[18:19], v[18:19], v[82:83] op_sel_hi:[1,0]
	v_pk_mul_f32 v[16:17], v[16:17], v[82:83] op_sel_hi:[1,0]
	v_pk_mul_f32 v[14:15], v[14:15], v[82:83] op_sel_hi:[1,0]
	v_pk_mul_f32 v[12:13], v[12:13], v[82:83] op_sel_hi:[1,0]
	v_pk_mul_f32 v[10:11], v[10:11], v[82:83] op_sel_hi:[1,0]
	v_pk_mul_f32 v[8:9], v[8:9], v[82:83] op_sel_hi:[1,0]
	v_pk_mul_f32 v[6:7], v[6:7], v[82:83] op_sel_hi:[1,0]
	v_pk_mul_f32 v[4:5], v[4:5], v[82:83] op_sel_hi:[1,0]
	v_pk_mul_f32 v[2:3], v[2:3], v[82:83] op_sel_hi:[1,0]
	v_pk_mul_f32 v[0:1], v[0:1], v[82:83] op_sel_hi:[1,0]
	v_mov_b64_e32 v[220:221], v[84:85]
	v_mov_b32_e32 v81, v80
	v_mov_b32_e32 v82, v80
	v_mov_b32_e32 v83, v80
	v_mov_b32_e32 v84, v80
	v_mov_b32_e32 v85, v80
	v_mov_b32_e32 v86, v80
	v_mov_b32_e32 v87, v80
	v_mov_b32_e32 v88, v80
	v_mov_b32_e32 v89, v80
	v_mov_b32_e32 v90, v80
	v_mov_b32_e32 v91, v80
	v_mov_b32_e32 v92, v80
	v_mov_b32_e32 v93, v80
	v_mov_b32_e32 v94, v80
	v_mov_b32_e32 v95, v80
	s_branch .Lmla_back1
